# barrier: the acquire invalidate is issued by idle wave 1 at block arrival (off thread 0's atomic/poll chain)
# speedup vs baseline: 1.0065x; 1.0065x over previous
.LBB0_8:
	s_or_b64 exec, exec, s[0:1]
	v_readfirstlane_b32 s98, v179
	s_lshr_b32 s98, s98, 6
	s_cmp_eq_u32 s98, 1
	s_cbranch_scc0 .Lbar_noinv
	buffer_inv sc1
	s_waitcnt vmcnt(0)
.Lbar_noinv:
	s_mov_b64 s[0:1], 0
	s_waitcnt lgkmcnt(0)
	s_barrier
